# GEMM K-loops: global-to-LDS loads issued before the fragment ds_reads in each memory block (longer load lead)
# baseline (speedup 1.0000x reference)
.LBB0_50:
	s_add_u32 s8, s58, 0xfffc0080
	s_addc_u32 s9, s59, -1
	s_add_i32 s10, 0, 0x10000
	s_cmp_eq_u32 s85, 12
	s_cselect_b32 s41, s53, s9
	s_cselect_b32 s40, s69, s8
	s_cselect_b32 s29, s51, s84
	s_cselect_b32 s28, s72, s73
	s_add_i32 s11, 0, 0x14000
	v_lshl_add_u64 v[210:211], s[58:59], 0, v[138:139]
	s_add_i32 m0, s61, 0xc000
	s_nop 0
	global_load_lds_dwordx4 v[210:211], off
	v_lshl_add_u64 v[210:211], s[58:59], 0, v[140:141]
	s_add_i32 m0, s61, 0xe000
	s_nop 0
	global_load_lds_dwordx4 v[210:211], off
	v_add_u32_e32 v158, s10, v150
	v_add_u32_e32 v174, s11, v150
	ds_read_b128 v[142:145], v158
	ds_read_b128 v[146:149], v158 offset:1024
	ds_read_b128 v[154:157], v158 offset:2048
	ds_read_b128 v[158:161], v158 offset:3072
	ds_read_b128 v[162:165], v174
	ds_read_b128 v[166:169], v174 offset:1024
	ds_read_b128 v[170:173], v174 offset:2048
	ds_read_b128 v[174:177], v174 offset:3072
	ds_read_b128 v[178:181], v153
	ds_read_b128 v[182:185], v153 offset:1024
	ds_read_b128 v[186:189], v153 offset:2048
	ds_read_b128 v[190:193], v153 offset:3072
	ds_read_b128 v[194:197], v153 offset:4096
	ds_read_b128 v[198:201], v153 offset:5120
	ds_read_b128 v[202:205], v153 offset:6144
	ds_read_b128 v[206:209], v153 offset:7168
	s_waitcnt vmcnt(8)
	s_waitcnt lgkmcnt(0)
	s_setprio 1
	s_barrier
	v_mfma_f32_16x16x32_bf16 v[126:129], v[142:145], v[178:181], v[126:129]
	v_mfma_f32_16x16x32_bf16 v[118:121], v[154:157], v[178:181], v[118:121]
	v_mfma_f32_16x16x32_bf16 v[110:113], v[142:145], v[186:189], v[110:113]
	v_mfma_f32_16x16x32_bf16 v[102:105], v[154:157], v[186:189], v[102:105]
	v_mfma_f32_16x16x32_bf16 v[94:97], v[142:145], v[194:197], v[94:97]
	v_mfma_f32_16x16x32_bf16 v[86:89], v[154:157], v[194:197], v[86:89]
	v_mfma_f32_16x16x32_bf16 v[78:81], v[142:145], v[202:205], v[78:81]
	v_mfma_f32_16x16x32_bf16 v[70:73], v[154:157], v[202:205], v[70:73]
	v_mfma_f32_16x16x32_bf16 v[126:129], v[146:149], v[182:185], v[126:129]
	v_mfma_f32_16x16x32_bf16 v[118:121], v[158:161], v[182:185], v[118:121]
	v_mfma_f32_16x16x32_bf16 v[110:113], v[146:149], v[190:193], v[110:113]
	v_mfma_f32_16x16x32_bf16 v[102:105], v[158:161], v[190:193], v[102:105]
	v_mfma_f32_16x16x32_bf16 v[94:97], v[146:149], v[198:201], v[94:97]
	v_mfma_f32_16x16x32_bf16 v[86:89], v[158:161], v[198:201], v[86:89]
	v_mfma_f32_16x16x32_bf16 v[78:81], v[146:149], v[206:209], v[78:81]
	v_mfma_f32_16x16x32_bf16 v[70:73], v[158:161], v[206:209], v[70:73]
	v_mfma_f32_16x16x32_bf16 v[122:125], v[162:165], v[178:181], v[122:125]
	v_mfma_f32_16x16x32_bf16 v[114:117], v[170:173], v[178:181], v[114:117]
	v_mfma_f32_16x16x32_bf16 v[106:109], v[162:165], v[186:189], v[106:109]
	v_mfma_f32_16x16x32_bf16 v[98:101], v[170:173], v[186:189], v[98:101]
	v_mfma_f32_16x16x32_bf16 v[90:93], v[162:165], v[194:197], v[90:93]
	v_mfma_f32_16x16x32_bf16 v[82:85], v[170:173], v[194:197], v[82:85]
	v_mfma_f32_16x16x32_bf16 v[74:77], v[162:165], v[202:205], v[74:77]
	v_mfma_f32_16x16x32_bf16 v[66:69], v[170:173], v[202:205], v[66:69]
	v_mfma_f32_16x16x32_bf16 v[122:125], v[166:169], v[182:185], v[122:125]
	v_mfma_f32_16x16x32_bf16 v[114:117], v[174:177], v[182:185], v[114:117]
	v_mfma_f32_16x16x32_bf16 v[106:109], v[166:169], v[190:193], v[106:109]
	v_mfma_f32_16x16x32_bf16 v[98:101], v[174:177], v[190:193], v[98:101]
	v_mfma_f32_16x16x32_bf16 v[90:93], v[166:169], v[198:201], v[90:93]
	v_mfma_f32_16x16x32_bf16 v[82:85], v[174:177], v[198:201], v[82:85]
	v_mfma_f32_16x16x32_bf16 v[74:77], v[166:169], v[206:209], v[74:77]
	v_mfma_f32_16x16x32_bf16 v[66:69], v[174:177], v[206:209], v[66:69]
	s_barrier
	s_setprio 0
	s_add_i32 s8, s10, s31
	v_lshl_add_u64 v[210:211], s[28:29], 0, v[130:131]
	s_mov_b32 m0, s8
	s_nop 0
	global_load_lds_dwordx4 v[210:211], off
	s_add_i32 m0, s8, 0x2000
	s_add_u32 s8, s28, 0x40000
	v_lshl_add_u64 v[212:213], s[28:29], 0, v[132:133]
	s_addc_u32 s9, s29, 0
	s_add_i32 s10, s11, s31
	global_load_lds_dwordx4 v[212:213], off
	v_lshl_add_u64 v[214:215], s[8:9], 0, v[130:131]
	s_mov_b32 m0, s10
	v_lshl_add_u64 v[216:217], s[40:41], 0, v[134:135]
	global_load_lds_dwordx4 v[214:215], off
	v_lshl_add_u64 v[214:215], s[8:9], 0, v[132:133]
	s_add_i32 m0, s10, 0x2000
	s_nop 0
	global_load_lds_dwordx4 v[214:215], off
	v_lshl_add_u64 v[214:215], s[40:41], 0, v[136:137]
	s_mov_b32 m0, s61
	s_nop 0
	global_load_lds_dwordx4 v[214:215], off
	s_mov_b32 m0, s62
	s_nop 0
	global_load_lds_dwordx4 v[216:217], off
	ds_read_b128 v[178:181], v153 offset:16384
	ds_read_b128 v[182:185], v153 offset:17408
	ds_read_b128 v[186:189], v153 offset:18432
	ds_read_b128 v[190:193], v153 offset:19456
	ds_read_b128 v[194:197], v153 offset:20480
	ds_read_b128 v[198:201], v153 offset:21504
	ds_read_b128 v[202:205], v153 offset:22528
	ds_read_b128 v[206:209], v153 offset:23552
	s_waitcnt vmcnt(8)
	s_waitcnt lgkmcnt(0)
	s_setprio 1
	s_barrier
	v_mfma_f32_16x16x32_bf16 v[62:65], v[142:145], v[178:181], v[62:65]
	v_mfma_f32_16x16x32_bf16 v[54:57], v[154:157], v[178:181], v[54:57]
	v_mfma_f32_16x16x32_bf16 v[46:49], v[142:145], v[186:189], v[46:49]
	v_mfma_f32_16x16x32_bf16 v[38:41], v[154:157], v[186:189], v[38:41]
	v_mfma_f32_16x16x32_bf16 v[30:33], v[142:145], v[194:197], v[30:33]
	v_mfma_f32_16x16x32_bf16 v[22:25], v[154:157], v[194:197], v[22:25]
	v_mfma_f32_16x16x32_bf16 v[14:17], v[142:145], v[202:205], v[14:17]
	v_mfma_f32_16x16x32_bf16 v[6:9], v[154:157], v[202:205], v[6:9]
	v_mfma_f32_16x16x32_bf16 v[62:65], v[146:149], v[182:185], v[62:65]
	v_mfma_f32_16x16x32_bf16 v[54:57], v[158:161], v[182:185], v[54:57]
	v_mfma_f32_16x16x32_bf16 v[46:49], v[146:149], v[190:193], v[46:49]
	v_mfma_f32_16x16x32_bf16 v[38:41], v[158:161], v[190:193], v[38:41]
	v_mfma_f32_16x16x32_bf16 v[30:33], v[146:149], v[198:201], v[30:33]
	v_mfma_f32_16x16x32_bf16 v[22:25], v[158:161], v[198:201], v[22:25]
	v_mfma_f32_16x16x32_bf16 v[14:17], v[146:149], v[206:209], v[14:17]
	v_mfma_f32_16x16x32_bf16 v[6:9], v[158:161], v[206:209], v[6:9]
	v_mfma_f32_16x16x32_bf16 v[58:61], v[162:165], v[178:181], v[58:61]
	v_mfma_f32_16x16x32_bf16 v[50:53], v[170:173], v[178:181], v[50:53]
	v_mfma_f32_16x16x32_bf16 v[42:45], v[162:165], v[186:189], v[42:45]
	v_mfma_f32_16x16x32_bf16 v[34:37], v[170:173], v[186:189], v[34:37]
	v_mfma_f32_16x16x32_bf16 v[26:29], v[162:165], v[194:197], v[26:29]
	v_mfma_f32_16x16x32_bf16 v[18:21], v[170:173], v[194:197], v[18:21]
	v_mfma_f32_16x16x32_bf16 v[10:13], v[162:165], v[202:205], v[10:13]
	v_mfma_f32_16x16x32_bf16 v[2:5], v[170:173], v[202:205], v[2:5]
	v_mfma_f32_16x16x32_bf16 v[58:61], v[166:169], v[182:185], v[58:61]
	v_mfma_f32_16x16x32_bf16 v[50:53], v[174:177], v[182:185], v[50:53]
	v_mfma_f32_16x16x32_bf16 v[42:45], v[166:169], v[190:193], v[42:45]
	v_mfma_f32_16x16x32_bf16 v[34:37], v[174:177], v[190:193], v[34:37]
	v_mfma_f32_16x16x32_bf16 v[26:29], v[166:169], v[198:201], v[26:29]
	v_mfma_f32_16x16x32_bf16 v[18:21], v[174:177], v[198:201], v[18:21]
	v_mfma_f32_16x16x32_bf16 v[10:13], v[166:169], v[206:209], v[10:13]
	v_mfma_f32_16x16x32_bf16 v[2:5], v[174:177], v[206:209], v[2:5]
	s_barrier
	s_setprio 0
	s_add_i32 s10, 0, 0x18000
	s_add_i32 s11, 0, 0x1c000
	s_add_u32 s8, s40, 0x40000
	s_addc_u32 s9, s41, 0
	s_mov_b32 m0, s63
	v_lshl_add_u64 v[218:219], s[8:9], 0, v[136:137]
	global_load_lds_dwordx4 v[218:219], off
	v_lshl_add_u64 v[218:219], s[8:9], 0, v[134:135]
	s_mov_b32 m0, s64
	s_nop 0
	global_load_lds_dwordx4 v[218:219], off
	v_add_u32_e32 v158, s10, v150
	v_add_u32_e32 v174, s11, v150
	ds_read_b128 v[142:145], v158
	ds_read_b128 v[146:149], v158 offset:1024
	ds_read_b128 v[154:157], v158 offset:2048
	ds_read_b128 v[158:161], v158 offset:3072
	ds_read_b128 v[162:165], v174
	ds_read_b128 v[166:169], v174 offset:1024
	ds_read_b128 v[170:173], v174 offset:2048
	ds_read_b128 v[174:177], v174 offset:3072
	ds_read_b128 v[178:181], v153 offset:32768
	ds_read_b128 v[182:185], v153 offset:33792
	ds_read_b128 v[186:189], v153 offset:34816
	ds_read_b128 v[190:193], v153 offset:35840
	ds_read_b128 v[194:197], v153 offset:36864
	ds_read_b128 v[198:201], v153 offset:37888
	ds_read_b128 v[202:205], v153 offset:38912
	ds_read_b128 v[206:209], v153 offset:39936
	s_waitcnt vmcnt(8)
	s_waitcnt lgkmcnt(0)
	s_setprio 1
	s_barrier
	v_mfma_f32_16x16x32_bf16 v[126:129], v[142:145], v[178:181], v[126:129]
	v_mfma_f32_16x16x32_bf16 v[118:121], v[154:157], v[178:181], v[118:121]
	v_mfma_f32_16x16x32_bf16 v[110:113], v[142:145], v[186:189], v[110:113]
	v_mfma_f32_16x16x32_bf16 v[102:105], v[154:157], v[186:189], v[102:105]
	v_mfma_f32_16x16x32_bf16 v[94:97], v[142:145], v[194:197], v[94:97]
	v_mfma_f32_16x16x32_bf16 v[86:89], v[154:157], v[194:197], v[86:89]
	v_mfma_f32_16x16x32_bf16 v[78:81], v[142:145], v[202:205], v[78:81]
	v_mfma_f32_16x16x32_bf16 v[70:73], v[154:157], v[202:205], v[70:73]
	v_mfma_f32_16x16x32_bf16 v[126:129], v[146:149], v[182:185], v[126:129]
	v_mfma_f32_16x16x32_bf16 v[118:121], v[158:161], v[182:185], v[118:121]
	v_mfma_f32_16x16x32_bf16 v[110:113], v[146:149], v[190:193], v[110:113]
	v_mfma_f32_16x16x32_bf16 v[102:105], v[158:161], v[190:193], v[102:105]
	v_mfma_f32_16x16x32_bf16 v[94:97], v[146:149], v[198:201], v[94:97]
	v_mfma_f32_16x16x32_bf16 v[86:89], v[158:161], v[198:201], v[86:89]
	v_mfma_f32_16x16x32_bf16 v[78:81], v[146:149], v[206:209], v[78:81]
	v_mfma_f32_16x16x32_bf16 v[70:73], v[158:161], v[206:209], v[70:73]
	v_mfma_f32_16x16x32_bf16 v[122:125], v[162:165], v[178:181], v[122:125]
	v_mfma_f32_16x16x32_bf16 v[114:117], v[170:173], v[178:181], v[114:117]
	v_mfma_f32_16x16x32_bf16 v[106:109], v[162:165], v[186:189], v[106:109]
	v_mfma_f32_16x16x32_bf16 v[98:101], v[170:173], v[186:189], v[98:101]
	v_mfma_f32_16x16x32_bf16 v[90:93], v[162:165], v[194:197], v[90:93]
	v_mfma_f32_16x16x32_bf16 v[82:85], v[170:173], v[194:197], v[82:85]
	v_mfma_f32_16x16x32_bf16 v[74:77], v[162:165], v[202:205], v[74:77]
	v_mfma_f32_16x16x32_bf16 v[66:69], v[170:173], v[202:205], v[66:69]
	v_mfma_f32_16x16x32_bf16 v[122:125], v[166:169], v[182:185], v[122:125]
	v_mfma_f32_16x16x32_bf16 v[114:117], v[174:177], v[182:185], v[114:117]
	v_mfma_f32_16x16x32_bf16 v[106:109], v[166:169], v[190:193], v[106:109]
	v_mfma_f32_16x16x32_bf16 v[98:101], v[174:177], v[190:193], v[98:101]
	v_mfma_f32_16x16x32_bf16 v[90:93], v[166:169], v[198:201], v[90:93]
	v_mfma_f32_16x16x32_bf16 v[82:85], v[174:177], v[198:201], v[82:85]
	v_mfma_f32_16x16x32_bf16 v[74:77], v[166:169], v[206:209], v[74:77]
	v_mfma_f32_16x16x32_bf16 v[66:69], v[174:177], v[206:209], v[66:69]
	s_barrier
	s_setprio 0
	s_add_i32 s8, s10, s31
	v_lshl_add_u64 v[210:211], v[210:211], 0, s[82:83]
	s_mov_b32 m0, s8
	s_nop 0
	global_load_lds_dwordx4 v[210:211], off
	s_add_i32 m0, s8, 0x2000
	s_add_u32 s8, s28, 0x40080
	v_lshl_add_u64 v[210:211], v[212:213], 0, s[82:83]
	s_addc_u32 s9, s29, 0
	s_add_i32 s10, s11, s31
	global_load_lds_dwordx4 v[210:211], off
	v_lshl_add_u64 v[210:211], s[8:9], 0, v[130:131]
	s_mov_b32 m0, s10
	s_nop 0
	global_load_lds_dwordx4 v[210:211], off
	v_lshl_add_u64 v[210:211], s[8:9], 0, v[132:133]
	s_add_i32 m0, s10, 0x2000
	s_nop 0
	global_load_lds_dwordx4 v[210:211], off
	v_lshl_add_u64 v[210:211], v[214:215], 0, s[82:83]
	s_mov_b32 m0, s65
	s_nop 0
	global_load_lds_dwordx4 v[210:211], off
	v_lshl_add_u64 v[210:211], v[216:217], 0, s[82:83]
	s_mov_b32 m0, s66
	s_nop 0
	global_load_lds_dwordx4 v[210:211], off
	ds_read_b128 v[178:181], v153 offset:49152
	ds_read_b128 v[182:185], v153 offset:50176
	ds_read_b128 v[186:189], v153 offset:51200
	ds_read_b128 v[190:193], v153 offset:52224
	ds_read_b128 v[194:197], v153 offset:53248
	ds_read_b128 v[198:201], v153 offset:54272
	ds_read_b128 v[202:205], v153 offset:55296
	ds_read_b128 v[206:209], v153 offset:56320
	s_waitcnt vmcnt(8)
	s_waitcnt lgkmcnt(0)
	s_setprio 1
	s_barrier
	v_mfma_f32_16x16x32_bf16 v[62:65], v[142:145], v[178:181], v[62:65]
	v_mfma_f32_16x16x32_bf16 v[54:57], v[154:157], v[178:181], v[54:57]
	v_mfma_f32_16x16x32_bf16 v[46:49], v[142:145], v[186:189], v[46:49]
	v_mfma_f32_16x16x32_bf16 v[38:41], v[154:157], v[186:189], v[38:41]
	v_mfma_f32_16x16x32_bf16 v[30:33], v[142:145], v[194:197], v[30:33]
	v_mfma_f32_16x16x32_bf16 v[22:25], v[154:157], v[194:197], v[22:25]
	v_mfma_f32_16x16x32_bf16 v[14:17], v[142:145], v[202:205], v[14:17]
	v_mfma_f32_16x16x32_bf16 v[6:9], v[154:157], v[202:205], v[6:9]
	v_mfma_f32_16x16x32_bf16 v[62:65], v[146:149], v[182:185], v[62:65]
	v_mfma_f32_16x16x32_bf16 v[54:57], v[158:161], v[182:185], v[54:57]
	v_mfma_f32_16x16x32_bf16 v[46:49], v[146:149], v[190:193], v[46:49]
	v_mfma_f32_16x16x32_bf16 v[38:41], v[158:161], v[190:193], v[38:41]
	v_mfma_f32_16x16x32_bf16 v[30:33], v[146:149], v[198:201], v[30:33]
	v_mfma_f32_16x16x32_bf16 v[22:25], v[158:161], v[198:201], v[22:25]
	v_mfma_f32_16x16x32_bf16 v[14:17], v[146:149], v[206:209], v[14:17]
	v_mfma_f32_16x16x32_bf16 v[6:9], v[158:161], v[206:209], v[6:9]
	v_mfma_f32_16x16x32_bf16 v[58:61], v[162:165], v[178:181], v[58:61]
	v_mfma_f32_16x16x32_bf16 v[50:53], v[170:173], v[178:181], v[50:53]
	v_mfma_f32_16x16x32_bf16 v[42:45], v[162:165], v[186:189], v[42:45]
	v_mfma_f32_16x16x32_bf16 v[34:37], v[170:173], v[186:189], v[34:37]
	v_mfma_f32_16x16x32_bf16 v[26:29], v[162:165], v[194:197], v[26:29]
	v_mfma_f32_16x16x32_bf16 v[18:21], v[170:173], v[194:197], v[18:21]
	v_mfma_f32_16x16x32_bf16 v[10:13], v[162:165], v[202:205], v[10:13]
	v_mfma_f32_16x16x32_bf16 v[2:5], v[170:173], v[202:205], v[2:5]
	v_mfma_f32_16x16x32_bf16 v[58:61], v[166:169], v[182:185], v[58:61]
	v_mfma_f32_16x16x32_bf16 v[50:53], v[174:177], v[182:185], v[50:53]
	v_mfma_f32_16x16x32_bf16 v[42:45], v[166:169], v[190:193], v[42:45]
	v_mfma_f32_16x16x32_bf16 v[34:37], v[174:177], v[190:193], v[34:37]
	v_mfma_f32_16x16x32_bf16 v[26:29], v[166:169], v[198:201], v[26:29]
	v_mfma_f32_16x16x32_bf16 v[18:21], v[174:177], v[198:201], v[18:21]
	v_mfma_f32_16x16x32_bf16 v[10:13], v[166:169], v[206:209], v[10:13]
	v_mfma_f32_16x16x32_bf16 v[2:5], v[174:177], v[206:209], v[2:5]
	s_barrier
	s_setprio 0
	s_add_i32 s85, s85, 2
	s_add_u32 s58, s58, 0x100
	s_addc_u32 s59, s59, 0
	s_add_u32 s73, s73, 0x100
	s_addc_u32 s84, s84, 0
	s_cmp_gt_u32 s85, 13
	s_cbranch_scc0 .LBB0_50
	s_and_b64 vcc, exec, s[48:49]
	s_cbranch_vccz .LBB0_53
	s_barrier

.LBB0_75:
	s_add_i32 s41, s28, 2
	s_add_u32 s8, s60, 0x80
	s_addc_u32 s9, s61, 0
	s_add_i32 s10, 0, 0x10000
	s_cmp_eq_u32 s84, s28
	s_cselect_b32 s29, s47, s9
	s_cselect_b32 s28, s46, s8
	s_cselect_b32 s9, s59, s40
	s_cselect_b32 s8, s58, s7
	s_add_i32 s11, 0, 0x14000
	v_lshl_add_u64 v[206:207], s[60:61], 0, v[194:195]
	s_add_i32 m0, s66, 0xc000
	s_nop 0
	global_load_lds_dwordx4 v[206:207], off
	v_lshl_add_u64 v[206:207], s[60:61], 0, v[196:197]
	s_add_i32 m0, s66, 0xe000
	s_nop 0
	global_load_lds_dwordx4 v[206:207], off
	v_add_u32_e32 v126, s10, v1
	v_add_u32_e32 v160, s11, v1
	ds_read_b128 v[98:101], v126
	ds_read_b128 v[102:105], v126 offset:1024
	ds_read_b128 v[122:125], v126 offset:2048
	ds_read_b128 v[126:129], v126 offset:3072
	ds_read_b128 v[144:147], v160
	ds_read_b128 v[148:151], v160 offset:1024
	ds_read_b128 v[156:159], v160 offset:2048
	ds_read_b128 v[160:163], v160 offset:3072
	ds_read_b128 v[164:167], v231
	ds_read_b128 v[168:171], v231 offset:1024
	ds_read_b128 v[172:175], v231 offset:2048
	ds_read_b128 v[176:179], v231 offset:3072
	ds_read_b128 v[180:183], v231 offset:4096
	ds_read_b128 v[184:187], v231 offset:5120
	ds_read_b128 v[198:201], v231 offset:6144
	ds_read_b128 v[202:205], v231 offset:7168
	s_waitcnt vmcnt(8)
	s_waitcnt lgkmcnt(0)
	s_setprio 1
	s_barrier
	v_mfma_f32_16x16x32_bf16 v[152:155], v[98:101], v[164:167], v[152:155]
	v_mfma_f32_16x16x32_bf16 v[140:143], v[122:125], v[164:167], v[140:143]
	v_mfma_f32_16x16x32_bf16 v[118:121], v[98:101], v[172:175], v[118:121]
	v_mfma_f32_16x16x32_bf16 v[114:117], v[122:125], v[172:175], v[114:117]
	v_mfma_f32_16x16x32_bf16 v[94:97], v[98:101], v[180:183], v[94:97]
	v_mfma_f32_16x16x32_bf16 v[90:93], v[122:125], v[180:183], v[90:93]
	v_mfma_f32_16x16x32_bf16 v[78:81], v[98:101], v[198:201], v[78:81]
	v_mfma_f32_16x16x32_bf16 v[74:77], v[122:125], v[198:201], v[74:77]
	v_mfma_f32_16x16x32_bf16 v[152:155], v[102:105], v[168:171], v[152:155]
	v_mfma_f32_16x16x32_bf16 v[140:143], v[126:129], v[168:171], v[140:143]
	v_mfma_f32_16x16x32_bf16 v[118:121], v[102:105], v[176:179], v[118:121]
	v_mfma_f32_16x16x32_bf16 v[114:117], v[126:129], v[176:179], v[114:117]
	v_mfma_f32_16x16x32_bf16 v[94:97], v[102:105], v[184:187], v[94:97]
	v_mfma_f32_16x16x32_bf16 v[90:93], v[126:129], v[184:187], v[90:93]
	v_mfma_f32_16x16x32_bf16 v[78:81], v[102:105], v[202:205], v[78:81]
	v_mfma_f32_16x16x32_bf16 v[74:77], v[126:129], v[202:205], v[74:77]
	v_mfma_f32_16x16x32_bf16 v[136:139], v[144:147], v[164:167], v[136:139]
	v_mfma_f32_16x16x32_bf16 v[132:135], v[156:159], v[164:167], v[132:135]
	v_mfma_f32_16x16x32_bf16 v[110:113], v[144:147], v[172:175], v[110:113]
	v_mfma_f32_16x16x32_bf16 v[106:109], v[156:159], v[172:175], v[106:109]
	v_mfma_f32_16x16x32_bf16 v[86:89], v[144:147], v[180:183], v[86:89]
	v_mfma_f32_16x16x32_bf16 v[82:85], v[156:159], v[180:183], v[82:85]
	v_mfma_f32_16x16x32_bf16 v[70:73], v[144:147], v[198:201], v[70:73]
	v_mfma_f32_16x16x32_bf16 v[66:69], v[156:159], v[198:201], v[66:69]
	v_mfma_f32_16x16x32_bf16 v[136:139], v[148:151], v[168:171], v[136:139]
	v_mfma_f32_16x16x32_bf16 v[132:135], v[160:163], v[168:171], v[132:135]
	v_mfma_f32_16x16x32_bf16 v[110:113], v[148:151], v[176:179], v[110:113]
	v_mfma_f32_16x16x32_bf16 v[106:109], v[160:163], v[176:179], v[106:109]
	v_mfma_f32_16x16x32_bf16 v[86:89], v[148:151], v[184:187], v[86:89]
	v_mfma_f32_16x16x32_bf16 v[82:85], v[160:163], v[184:187], v[82:85]
	v_mfma_f32_16x16x32_bf16 v[70:73], v[148:151], v[202:205], v[70:73]
	v_mfma_f32_16x16x32_bf16 v[66:69], v[160:163], v[202:205], v[66:69]
	s_barrier
	s_setprio 0
	s_add_i32 s10, s10, s64
	v_lshl_add_u64 v[206:207], s[8:9], 0, v[130:131]
	s_mov_b32 m0, s10
	s_nop 0
	global_load_lds_dwordx4 v[206:207], off
	s_add_i32 m0, s10, 0x2000
	v_lshl_add_u64 v[208:209], s[8:9], 0, v[188:189]
	s_add_u32 s8, s8, s48
	s_addc_u32 s9, s9, 0
	s_add_i32 s10, s11, s64
	global_load_lds_dwordx4 v[208:209], off
	v_lshl_add_u64 v[210:211], s[8:9], 0, v[130:131]
	s_mov_b32 m0, s10
	v_lshl_add_u64 v[212:213], s[8:9], 0, v[188:189]
	global_load_lds_dwordx4 v[210:211], off
	s_add_i32 m0, s10, 0x2000
	v_lshl_add_u64 v[214:215], s[28:29], 0, v[192:193]
	global_load_lds_dwordx4 v[212:213], off
	s_mov_b32 m0, s66
	v_lshl_add_u64 v[216:217], s[28:29], 0, v[190:191]
	global_load_lds_dwordx4 v[214:215], off
	s_mov_b32 m0, s67
	s_nop 0
	global_load_lds_dwordx4 v[216:217], off
	ds_read_b128 v[164:167], v231 offset:16384
	ds_read_b128 v[168:171], v231 offset:17408
	ds_read_b128 v[172:175], v231 offset:18432
	ds_read_b128 v[176:179], v231 offset:19456
	ds_read_b128 v[180:183], v231 offset:20480
	ds_read_b128 v[184:187], v231 offset:21504
	ds_read_b128 v[198:201], v231 offset:22528
	ds_read_b128 v[202:205], v231 offset:23552
	s_waitcnt vmcnt(8)
	s_waitcnt lgkmcnt(0)
	s_setprio 1
	s_barrier
	v_mfma_f32_16x16x32_bf16 v[62:65], v[98:101], v[164:167], v[62:65]
	v_mfma_f32_16x16x32_bf16 v[58:61], v[122:125], v[164:167], v[58:61]
	v_mfma_f32_16x16x32_bf16 v[46:49], v[98:101], v[172:175], v[46:49]
	v_mfma_f32_16x16x32_bf16 v[42:45], v[122:125], v[172:175], v[42:45]
	v_mfma_f32_16x16x32_bf16 v[30:33], v[98:101], v[180:183], v[30:33]
	v_mfma_f32_16x16x32_bf16 v[26:29], v[122:125], v[180:183], v[26:29]
	v_mfma_f32_16x16x32_bf16 v[14:17], v[98:101], v[198:201], v[14:17]
	v_mfma_f32_16x16x32_bf16 v[10:13], v[122:125], v[198:201], v[10:13]
	v_mfma_f32_16x16x32_bf16 v[62:65], v[102:105], v[168:171], v[62:65]
	v_mfma_f32_16x16x32_bf16 v[58:61], v[126:129], v[168:171], v[58:61]
	v_mfma_f32_16x16x32_bf16 v[46:49], v[102:105], v[176:179], v[46:49]
	v_mfma_f32_16x16x32_bf16 v[42:45], v[126:129], v[176:179], v[42:45]
	v_mfma_f32_16x16x32_bf16 v[30:33], v[102:105], v[184:187], v[30:33]
	v_mfma_f32_16x16x32_bf16 v[26:29], v[126:129], v[184:187], v[26:29]
	v_mfma_f32_16x16x32_bf16 v[14:17], v[102:105], v[202:205], v[14:17]
	v_mfma_f32_16x16x32_bf16 v[10:13], v[126:129], v[202:205], v[10:13]
	v_mfma_f32_16x16x32_bf16 v[54:57], v[144:147], v[164:167], v[54:57]
	v_mfma_f32_16x16x32_bf16 v[50:53], v[156:159], v[164:167], v[50:53]
	v_mfma_f32_16x16x32_bf16 v[38:41], v[144:147], v[172:175], v[38:41]
	v_mfma_f32_16x16x32_bf16 v[34:37], v[156:159], v[172:175], v[34:37]
	v_mfma_f32_16x16x32_bf16 v[22:25], v[144:147], v[180:183], v[22:25]
	v_mfma_f32_16x16x32_bf16 v[18:21], v[156:159], v[180:183], v[18:21]
	v_mfma_f32_16x16x32_bf16 v[6:9], v[144:147], v[198:201], v[6:9]
	v_mfma_f32_16x16x32_bf16 v[2:5], v[156:159], v[198:201], v[2:5]
	v_mfma_f32_16x16x32_bf16 v[54:57], v[148:151], v[168:171], v[54:57]
	v_mfma_f32_16x16x32_bf16 v[50:53], v[160:163], v[168:171], v[50:53]
	v_mfma_f32_16x16x32_bf16 v[38:41], v[148:151], v[176:179], v[38:41]
	v_mfma_f32_16x16x32_bf16 v[34:37], v[160:163], v[176:179], v[34:37]
	v_mfma_f32_16x16x32_bf16 v[22:25], v[148:151], v[184:187], v[22:25]
	v_mfma_f32_16x16x32_bf16 v[18:21], v[160:163], v[184:187], v[18:21]
	v_mfma_f32_16x16x32_bf16 v[6:9], v[148:151], v[202:205], v[6:9]
	v_mfma_f32_16x16x32_bf16 v[2:5], v[160:163], v[202:205], v[2:5]
	s_barrier
	s_setprio 0
	s_add_i32 s10, 0, 0x18000
	s_add_i32 s11, 0, 0x1c000
	s_add_u32 s8, s28, s48
	s_addc_u32 s9, s29, 0
	s_mov_b32 m0, s68
	v_lshl_add_u64 v[218:219], s[8:9], 0, v[192:193]
	global_load_lds_dwordx4 v[218:219], off
	v_lshl_add_u64 v[218:219], s[8:9], 0, v[190:191]
	s_mov_b32 m0, s69
	s_nop 0
	global_load_lds_dwordx4 v[218:219], off
	v_add_u32_e32 v126, s10, v1
	v_add_u32_e32 v160, s11, v1
	ds_read_b128 v[98:101], v126
	ds_read_b128 v[102:105], v126 offset:1024
	ds_read_b128 v[122:125], v126 offset:2048
	ds_read_b128 v[126:129], v126 offset:3072
	ds_read_b128 v[144:147], v160
	ds_read_b128 v[148:151], v160 offset:1024
	ds_read_b128 v[156:159], v160 offset:2048
	ds_read_b128 v[160:163], v160 offset:3072
	ds_read_b128 v[164:167], v231 offset:32768
	ds_read_b128 v[168:171], v231 offset:33792
	ds_read_b128 v[172:175], v231 offset:34816
	ds_read_b128 v[176:179], v231 offset:35840
	ds_read_b128 v[180:183], v231 offset:36864
	ds_read_b128 v[184:187], v231 offset:37888
	ds_read_b128 v[198:201], v231 offset:38912
	ds_read_b128 v[202:205], v231 offset:39936
	s_waitcnt vmcnt(8)
	s_waitcnt lgkmcnt(0)
	s_setprio 1
	s_barrier
	v_mfma_f32_16x16x32_bf16 v[152:155], v[98:101], v[164:167], v[152:155]
	v_mfma_f32_16x16x32_bf16 v[140:143], v[122:125], v[164:167], v[140:143]
	v_mfma_f32_16x16x32_bf16 v[118:121], v[98:101], v[172:175], v[118:121]
	v_mfma_f32_16x16x32_bf16 v[114:117], v[122:125], v[172:175], v[114:117]
	v_mfma_f32_16x16x32_bf16 v[94:97], v[98:101], v[180:183], v[94:97]
	v_mfma_f32_16x16x32_bf16 v[90:93], v[122:125], v[180:183], v[90:93]
	v_mfma_f32_16x16x32_bf16 v[78:81], v[98:101], v[198:201], v[78:81]
	v_mfma_f32_16x16x32_bf16 v[74:77], v[122:125], v[198:201], v[74:77]
	v_mfma_f32_16x16x32_bf16 v[152:155], v[102:105], v[168:171], v[152:155]
	v_mfma_f32_16x16x32_bf16 v[140:143], v[126:129], v[168:171], v[140:143]
	v_mfma_f32_16x16x32_bf16 v[118:121], v[102:105], v[176:179], v[118:121]
	v_mfma_f32_16x16x32_bf16 v[114:117], v[126:129], v[176:179], v[114:117]
	v_mfma_f32_16x16x32_bf16 v[94:97], v[102:105], v[184:187], v[94:97]
	v_mfma_f32_16x16x32_bf16 v[90:93], v[126:129], v[184:187], v[90:93]
	v_mfma_f32_16x16x32_bf16 v[78:81], v[102:105], v[202:205], v[78:81]
	v_mfma_f32_16x16x32_bf16 v[74:77], v[126:129], v[202:205], v[74:77]
	v_mfma_f32_16x16x32_bf16 v[136:139], v[144:147], v[164:167], v[136:139]
	v_mfma_f32_16x16x32_bf16 v[132:135], v[156:159], v[164:167], v[132:135]
	v_mfma_f32_16x16x32_bf16 v[110:113], v[144:147], v[172:175], v[110:113]
	v_mfma_f32_16x16x32_bf16 v[106:109], v[156:159], v[172:175], v[106:109]
	v_mfma_f32_16x16x32_bf16 v[86:89], v[144:147], v[180:183], v[86:89]
	v_mfma_f32_16x16x32_bf16 v[82:85], v[156:159], v[180:183], v[82:85]
	v_mfma_f32_16x16x32_bf16 v[70:73], v[144:147], v[198:201], v[70:73]
	v_mfma_f32_16x16x32_bf16 v[66:69], v[156:159], v[198:201], v[66:69]
	v_mfma_f32_16x16x32_bf16 v[136:139], v[148:151], v[168:171], v[136:139]
	v_mfma_f32_16x16x32_bf16 v[132:135], v[160:163], v[168:171], v[132:135]
	v_mfma_f32_16x16x32_bf16 v[110:113], v[148:151], v[176:179], v[110:113]
	v_mfma_f32_16x16x32_bf16 v[106:109], v[160:163], v[176:179], v[106:109]
	v_mfma_f32_16x16x32_bf16 v[86:89], v[148:151], v[184:187], v[86:89]
	v_mfma_f32_16x16x32_bf16 v[82:85], v[160:163], v[184:187], v[82:85]
	v_mfma_f32_16x16x32_bf16 v[70:73], v[148:151], v[202:205], v[70:73]
	v_mfma_f32_16x16x32_bf16 v[66:69], v[160:163], v[202:205], v[66:69]
	s_barrier
	s_setprio 0
	s_add_i32 s8, s10, s64
	v_lshl_add_u64 v[206:207], v[206:207], 0, s[82:83]
	s_mov_b32 m0, s8
	s_nop 0
	global_load_lds_dwordx4 v[206:207], off
	v_lshl_add_u64 v[206:207], v[208:209], 0, s[82:83]
	s_add_i32 m0, s8, 0x2000
	s_add_i32 s8, s11, s64
	global_load_lds_dwordx4 v[206:207], off
	v_lshl_add_u64 v[206:207], v[210:211], 0, s[82:83]
	s_mov_b32 m0, s8
	s_nop 0
	global_load_lds_dwordx4 v[206:207], off
	v_lshl_add_u64 v[206:207], v[212:213], 0, s[82:83]
	s_add_i32 m0, s8, 0x2000
	s_nop 0
	global_load_lds_dwordx4 v[206:207], off
	v_lshl_add_u64 v[206:207], v[214:215], 0, s[82:83]
	s_mov_b32 m0, s85
	s_nop 0
	global_load_lds_dwordx4 v[206:207], off
	v_lshl_add_u64 v[206:207], v[216:217], 0, s[82:83]
	s_mov_b32 m0, s88
	s_nop 0
	global_load_lds_dwordx4 v[206:207], off
	ds_read_b128 v[164:167], v231 offset:49152
	ds_read_b128 v[168:171], v231 offset:50176
	ds_read_b128 v[172:175], v231 offset:51200
	ds_read_b128 v[176:179], v231 offset:52224
	ds_read_b128 v[180:183], v231 offset:53248
	ds_read_b128 v[184:187], v231 offset:54272
	ds_read_b128 v[198:201], v231 offset:55296
	ds_read_b128 v[202:205], v231 offset:56320
	s_waitcnt vmcnt(8)
	s_waitcnt lgkmcnt(0)
	s_setprio 1
	s_barrier
	v_mfma_f32_16x16x32_bf16 v[62:65], v[98:101], v[164:167], v[62:65]
	v_mfma_f32_16x16x32_bf16 v[58:61], v[122:125], v[164:167], v[58:61]
	v_mfma_f32_16x16x32_bf16 v[46:49], v[98:101], v[172:175], v[46:49]
	v_mfma_f32_16x16x32_bf16 v[42:45], v[122:125], v[172:175], v[42:45]
	v_mfma_f32_16x16x32_bf16 v[30:33], v[98:101], v[180:183], v[30:33]
	v_mfma_f32_16x16x32_bf16 v[26:29], v[122:125], v[180:183], v[26:29]
	v_mfma_f32_16x16x32_bf16 v[14:17], v[98:101], v[198:201], v[14:17]
	v_mfma_f32_16x16x32_bf16 v[10:13], v[122:125], v[198:201], v[10:13]
	v_mfma_f32_16x16x32_bf16 v[62:65], v[102:105], v[168:171], v[62:65]
	v_mfma_f32_16x16x32_bf16 v[58:61], v[126:129], v[168:171], v[58:61]
	v_mfma_f32_16x16x32_bf16 v[46:49], v[102:105], v[176:179], v[46:49]
	v_mfma_f32_16x16x32_bf16 v[42:45], v[126:129], v[176:179], v[42:45]
	v_mfma_f32_16x16x32_bf16 v[30:33], v[102:105], v[184:187], v[30:33]
	v_mfma_f32_16x16x32_bf16 v[26:29], v[126:129], v[184:187], v[26:29]
	v_mfma_f32_16x16x32_bf16 v[14:17], v[102:105], v[202:205], v[14:17]
	v_mfma_f32_16x16x32_bf16 v[10:13], v[126:129], v[202:205], v[10:13]
	v_mfma_f32_16x16x32_bf16 v[54:57], v[144:147], v[164:167], v[54:57]
	v_mfma_f32_16x16x32_bf16 v[50:53], v[156:159], v[164:167], v[50:53]
	v_mfma_f32_16x16x32_bf16 v[38:41], v[144:147], v[172:175], v[38:41]
	v_mfma_f32_16x16x32_bf16 v[34:37], v[156:159], v[172:175], v[34:37]
	v_mfma_f32_16x16x32_bf16 v[22:25], v[144:147], v[180:183], v[22:25]
	v_mfma_f32_16x16x32_bf16 v[18:21], v[156:159], v[180:183], v[18:21]
	v_mfma_f32_16x16x32_bf16 v[6:9], v[144:147], v[198:201], v[6:9]
	v_mfma_f32_16x16x32_bf16 v[2:5], v[156:159], v[198:201], v[2:5]
	v_mfma_f32_16x16x32_bf16 v[54:57], v[148:151], v[168:171], v[54:57]
	v_mfma_f32_16x16x32_bf16 v[50:53], v[160:163], v[168:171], v[50:53]
	v_mfma_f32_16x16x32_bf16 v[38:41], v[148:151], v[176:179], v[38:41]
	v_mfma_f32_16x16x32_bf16 v[34:37], v[160:163], v[176:179], v[34:37]
	v_mfma_f32_16x16x32_bf16 v[22:25], v[148:151], v[184:187], v[22:25]
	v_mfma_f32_16x16x32_bf16 v[18:21], v[160:163], v[184:187], v[18:21]
	v_mfma_f32_16x16x32_bf16 v[6:9], v[148:151], v[202:205], v[6:9]
	v_mfma_f32_16x16x32_bf16 v[2:5], v[160:163], v[202:205], v[2:5]
	s_barrier
	s_setprio 0
	s_add_u32 s60, s60, 0x100
	s_addc_u32 s61, s61, 0
	s_add_u32 s7, s7, 0x100
	s_addc_u32 s40, s40, 0
	s_cmp_ge_u32 s41, s73
	s_mov_b32 s28, s41
	s_cbranch_scc0 .LBB0_75
	s_and_b64 vcc, exec, s[54:55]
	s_cbranch_vccz .LBB0_78
	s_barrier

.LBB0_497:
	s_add_u32 s8, s60, 0xfffc0080
	s_addc_u32 s9, s61, -1
	s_add_i32 s10, 0, 0x10000
	s_cmp_eq_u32 s84, 12
	s_cselect_b32 s41, s55, s9
	s_cselect_b32 s40, s72, s8
	s_cselect_b32 s29, s53, s77
	s_cselect_b32 s28, s73, s76
	s_add_i32 s11, 0, 0x14000
	v_lshl_add_u64 v[210:211], s[60:61], 0, v[138:139]
	s_add_i32 m0, s62, 0xc000
	s_nop 0
	global_load_lds_dwordx4 v[210:211], off
	v_lshl_add_u64 v[210:211], s[60:61], 0, v[140:141]
	s_add_i32 m0, s62, 0xe000
	s_nop 0
	global_load_lds_dwordx4 v[210:211], off
	v_add_u32_e32 v158, s10, v1
	v_add_u32_e32 v174, s11, v1
	ds_read_b128 v[146:149], v158
	ds_read_b128 v[150:153], v158 offset:1024
	ds_read_b128 v[154:157], v158 offset:2048
	ds_read_b128 v[158:161], v158 offset:3072
	ds_read_b128 v[162:165], v174
	ds_read_b128 v[166:169], v174 offset:1024
	ds_read_b128 v[170:173], v174 offset:2048
	ds_read_b128 v[174:177], v174 offset:3072
	ds_read_b128 v[178:181], v145
	ds_read_b128 v[182:185], v145 offset:1024
	ds_read_b128 v[186:189], v145 offset:2048
	ds_read_b128 v[190:193], v145 offset:3072
	ds_read_b128 v[194:197], v145 offset:4096
	ds_read_b128 v[198:201], v145 offset:5120
	ds_read_b128 v[202:205], v145 offset:6144
	ds_read_b128 v[206:209], v145 offset:7168
	s_waitcnt vmcnt(8)
	s_waitcnt lgkmcnt(0)
	s_setprio 1
	s_barrier
	v_mfma_f32_16x16x32_bf16 v[126:129], v[146:149], v[178:181], v[126:129]
	v_mfma_f32_16x16x32_bf16 v[122:125], v[154:157], v[178:181], v[122:125]
	v_mfma_f32_16x16x32_bf16 v[110:113], v[146:149], v[186:189], v[110:113]
	v_mfma_f32_16x16x32_bf16 v[106:109], v[154:157], v[186:189], v[106:109]
	v_mfma_f32_16x16x32_bf16 v[94:97], v[146:149], v[194:197], v[94:97]
	v_mfma_f32_16x16x32_bf16 v[90:93], v[154:157], v[194:197], v[90:93]
	v_mfma_f32_16x16x32_bf16 v[78:81], v[146:149], v[202:205], v[78:81]
	v_mfma_f32_16x16x32_bf16 v[74:77], v[154:157], v[202:205], v[74:77]
	v_mfma_f32_16x16x32_bf16 v[126:129], v[150:153], v[182:185], v[126:129]
	v_mfma_f32_16x16x32_bf16 v[122:125], v[158:161], v[182:185], v[122:125]
	v_mfma_f32_16x16x32_bf16 v[110:113], v[150:153], v[190:193], v[110:113]
	v_mfma_f32_16x16x32_bf16 v[106:109], v[158:161], v[190:193], v[106:109]
	v_mfma_f32_16x16x32_bf16 v[94:97], v[150:153], v[198:201], v[94:97]
	v_mfma_f32_16x16x32_bf16 v[90:93], v[158:161], v[198:201], v[90:93]
	v_mfma_f32_16x16x32_bf16 v[78:81], v[150:153], v[206:209], v[78:81]
	v_mfma_f32_16x16x32_bf16 v[74:77], v[158:161], v[206:209], v[74:77]
	v_mfma_f32_16x16x32_bf16 v[118:121], v[162:165], v[178:181], v[118:121]
	v_mfma_f32_16x16x32_bf16 v[114:117], v[170:173], v[178:181], v[114:117]
	v_mfma_f32_16x16x32_bf16 v[102:105], v[162:165], v[186:189], v[102:105]
	v_mfma_f32_16x16x32_bf16 v[98:101], v[170:173], v[186:189], v[98:101]
	v_mfma_f32_16x16x32_bf16 v[86:89], v[162:165], v[194:197], v[86:89]
	v_mfma_f32_16x16x32_bf16 v[82:85], v[170:173], v[194:197], v[82:85]
	v_mfma_f32_16x16x32_bf16 v[70:73], v[162:165], v[202:205], v[70:73]
	v_mfma_f32_16x16x32_bf16 v[66:69], v[170:173], v[202:205], v[66:69]
	v_mfma_f32_16x16x32_bf16 v[118:121], v[166:169], v[182:185], v[118:121]
	v_mfma_f32_16x16x32_bf16 v[114:117], v[174:177], v[182:185], v[114:117]
	v_mfma_f32_16x16x32_bf16 v[102:105], v[166:169], v[190:193], v[102:105]
	v_mfma_f32_16x16x32_bf16 v[98:101], v[174:177], v[190:193], v[98:101]
	v_mfma_f32_16x16x32_bf16 v[86:89], v[166:169], v[198:201], v[86:89]
	v_mfma_f32_16x16x32_bf16 v[82:85], v[174:177], v[198:201], v[82:85]
	v_mfma_f32_16x16x32_bf16 v[70:73], v[166:169], v[206:209], v[70:73]
	v_mfma_f32_16x16x32_bf16 v[66:69], v[174:177], v[206:209], v[66:69]
	s_barrier
	s_setprio 0
	s_add_i32 s8, s10, s34
	v_lshl_add_u64 v[210:211], s[28:29], 0, v[130:131]
	s_mov_b32 m0, s8
	s_nop 0
	global_load_lds_dwordx4 v[210:211], off
	s_add_i32 m0, s8, 0x2000
	s_add_u32 s8, s28, 0x40000
	v_lshl_add_u64 v[212:213], s[28:29], 0, v[132:133]
	s_addc_u32 s9, s29, 0
	s_add_i32 s10, s11, s34
	global_load_lds_dwordx4 v[212:213], off
	v_lshl_add_u64 v[214:215], s[8:9], 0, v[130:131]
	s_mov_b32 m0, s10
	v_lshl_add_u64 v[216:217], s[40:41], 0, v[134:135]
	global_load_lds_dwordx4 v[214:215], off
	v_lshl_add_u64 v[214:215], s[8:9], 0, v[132:133]
	s_add_i32 m0, s10, 0x2000
	s_nop 0
	global_load_lds_dwordx4 v[214:215], off
	v_lshl_add_u64 v[214:215], s[40:41], 0, v[136:137]
	s_mov_b32 m0, s62
	s_nop 0
	global_load_lds_dwordx4 v[214:215], off
	s_mov_b32 m0, s63
	s_nop 0
	global_load_lds_dwordx4 v[216:217], off
	ds_read_b128 v[178:181], v145 offset:16384
	ds_read_b128 v[182:185], v145 offset:17408
	ds_read_b128 v[186:189], v145 offset:18432
	ds_read_b128 v[190:193], v145 offset:19456
	ds_read_b128 v[194:197], v145 offset:20480
	ds_read_b128 v[198:201], v145 offset:21504
	ds_read_b128 v[202:205], v145 offset:22528
	ds_read_b128 v[206:209], v145 offset:23552
	s_waitcnt vmcnt(8)
	s_waitcnt lgkmcnt(0)
	s_setprio 1
	s_barrier
	v_mfma_f32_16x16x32_bf16 v[62:65], v[146:149], v[178:181], v[62:65]
	v_mfma_f32_16x16x32_bf16 v[58:61], v[154:157], v[178:181], v[58:61]
	v_mfma_f32_16x16x32_bf16 v[46:49], v[146:149], v[186:189], v[46:49]
	v_mfma_f32_16x16x32_bf16 v[42:45], v[154:157], v[186:189], v[42:45]
	v_mfma_f32_16x16x32_bf16 v[30:33], v[146:149], v[194:197], v[30:33]
	v_mfma_f32_16x16x32_bf16 v[26:29], v[154:157], v[194:197], v[26:29]
	v_mfma_f32_16x16x32_bf16 v[14:17], v[146:149], v[202:205], v[14:17]
	v_mfma_f32_16x16x32_bf16 v[10:13], v[154:157], v[202:205], v[10:13]
	v_mfma_f32_16x16x32_bf16 v[62:65], v[150:153], v[182:185], v[62:65]
	v_mfma_f32_16x16x32_bf16 v[58:61], v[158:161], v[182:185], v[58:61]
	v_mfma_f32_16x16x32_bf16 v[46:49], v[150:153], v[190:193], v[46:49]
	v_mfma_f32_16x16x32_bf16 v[42:45], v[158:161], v[190:193], v[42:45]
	v_mfma_f32_16x16x32_bf16 v[30:33], v[150:153], v[198:201], v[30:33]
	v_mfma_f32_16x16x32_bf16 v[26:29], v[158:161], v[198:201], v[26:29]
	v_mfma_f32_16x16x32_bf16 v[14:17], v[150:153], v[206:209], v[14:17]
	v_mfma_f32_16x16x32_bf16 v[10:13], v[158:161], v[206:209], v[10:13]
	v_mfma_f32_16x16x32_bf16 v[54:57], v[162:165], v[178:181], v[54:57]
	v_mfma_f32_16x16x32_bf16 v[50:53], v[170:173], v[178:181], v[50:53]
	v_mfma_f32_16x16x32_bf16 v[38:41], v[162:165], v[186:189], v[38:41]
	v_mfma_f32_16x16x32_bf16 v[34:37], v[170:173], v[186:189], v[34:37]
	v_mfma_f32_16x16x32_bf16 v[22:25], v[162:165], v[194:197], v[22:25]
	v_mfma_f32_16x16x32_bf16 v[18:21], v[170:173], v[194:197], v[18:21]
	v_mfma_f32_16x16x32_bf16 v[6:9], v[162:165], v[202:205], v[6:9]
	v_mfma_f32_16x16x32_bf16 v[2:5], v[170:173], v[202:205], v[2:5]
	v_mfma_f32_16x16x32_bf16 v[54:57], v[166:169], v[182:185], v[54:57]
	v_mfma_f32_16x16x32_bf16 v[50:53], v[174:177], v[182:185], v[50:53]
	v_mfma_f32_16x16x32_bf16 v[38:41], v[166:169], v[190:193], v[38:41]
	v_mfma_f32_16x16x32_bf16 v[34:37], v[174:177], v[190:193], v[34:37]
	v_mfma_f32_16x16x32_bf16 v[22:25], v[166:169], v[198:201], v[22:25]
	v_mfma_f32_16x16x32_bf16 v[18:21], v[174:177], v[198:201], v[18:21]
	v_mfma_f32_16x16x32_bf16 v[6:9], v[166:169], v[206:209], v[6:9]
	v_mfma_f32_16x16x32_bf16 v[2:5], v[174:177], v[206:209], v[2:5]
	s_barrier
	s_setprio 0
	s_add_i32 s10, 0, 0x18000
	s_add_i32 s11, 0, 0x1c000
	s_add_u32 s8, s40, 0x40000
	s_addc_u32 s9, s41, 0
	s_mov_b32 m0, s64
	v_lshl_add_u64 v[218:219], s[8:9], 0, v[136:137]
	global_load_lds_dwordx4 v[218:219], off
	v_lshl_add_u64 v[218:219], s[8:9], 0, v[134:135]
	s_mov_b32 m0, s65
	s_nop 0
	global_load_lds_dwordx4 v[218:219], off
	v_add_u32_e32 v158, s10, v1
	v_add_u32_e32 v174, s11, v1
	ds_read_b128 v[146:149], v158
	ds_read_b128 v[150:153], v158 offset:1024
	ds_read_b128 v[154:157], v158 offset:2048
	ds_read_b128 v[158:161], v158 offset:3072
	ds_read_b128 v[162:165], v174
	ds_read_b128 v[166:169], v174 offset:1024
	ds_read_b128 v[170:173], v174 offset:2048
	ds_read_b128 v[174:177], v174 offset:3072
	ds_read_b128 v[178:181], v145 offset:32768
	ds_read_b128 v[182:185], v145 offset:33792
	ds_read_b128 v[186:189], v145 offset:34816
	ds_read_b128 v[190:193], v145 offset:35840
	ds_read_b128 v[194:197], v145 offset:36864
	ds_read_b128 v[198:201], v145 offset:37888
	ds_read_b128 v[202:205], v145 offset:38912
	ds_read_b128 v[206:209], v145 offset:39936
	s_waitcnt vmcnt(8)
	s_waitcnt lgkmcnt(0)
	s_setprio 1
	s_barrier
	v_mfma_f32_16x16x32_bf16 v[126:129], v[146:149], v[178:181], v[126:129]
	v_mfma_f32_16x16x32_bf16 v[122:125], v[154:157], v[178:181], v[122:125]
	v_mfma_f32_16x16x32_bf16 v[110:113], v[146:149], v[186:189], v[110:113]
	v_mfma_f32_16x16x32_bf16 v[106:109], v[154:157], v[186:189], v[106:109]
	v_mfma_f32_16x16x32_bf16 v[94:97], v[146:149], v[194:197], v[94:97]
	v_mfma_f32_16x16x32_bf16 v[90:93], v[154:157], v[194:197], v[90:93]
	v_mfma_f32_16x16x32_bf16 v[78:81], v[146:149], v[202:205], v[78:81]
	v_mfma_f32_16x16x32_bf16 v[74:77], v[154:157], v[202:205], v[74:77]
	v_mfma_f32_16x16x32_bf16 v[126:129], v[150:153], v[182:185], v[126:129]
	v_mfma_f32_16x16x32_bf16 v[122:125], v[158:161], v[182:185], v[122:125]
	v_mfma_f32_16x16x32_bf16 v[110:113], v[150:153], v[190:193], v[110:113]
	v_mfma_f32_16x16x32_bf16 v[106:109], v[158:161], v[190:193], v[106:109]
	v_mfma_f32_16x16x32_bf16 v[94:97], v[150:153], v[198:201], v[94:97]
	v_mfma_f32_16x16x32_bf16 v[90:93], v[158:161], v[198:201], v[90:93]
	v_mfma_f32_16x16x32_bf16 v[78:81], v[150:153], v[206:209], v[78:81]
	v_mfma_f32_16x16x32_bf16 v[74:77], v[158:161], v[206:209], v[74:77]
	v_mfma_f32_16x16x32_bf16 v[118:121], v[162:165], v[178:181], v[118:121]
	v_mfma_f32_16x16x32_bf16 v[114:117], v[170:173], v[178:181], v[114:117]
	v_mfma_f32_16x16x32_bf16 v[102:105], v[162:165], v[186:189], v[102:105]
	v_mfma_f32_16x16x32_bf16 v[98:101], v[170:173], v[186:189], v[98:101]
	v_mfma_f32_16x16x32_bf16 v[86:89], v[162:165], v[194:197], v[86:89]
	v_mfma_f32_16x16x32_bf16 v[82:85], v[170:173], v[194:197], v[82:85]
	v_mfma_f32_16x16x32_bf16 v[70:73], v[162:165], v[202:205], v[70:73]
	v_mfma_f32_16x16x32_bf16 v[66:69], v[170:173], v[202:205], v[66:69]
	v_mfma_f32_16x16x32_bf16 v[118:121], v[166:169], v[182:185], v[118:121]
	v_mfma_f32_16x16x32_bf16 v[114:117], v[174:177], v[182:185], v[114:117]
	v_mfma_f32_16x16x32_bf16 v[102:105], v[166:169], v[190:193], v[102:105]
	v_mfma_f32_16x16x32_bf16 v[98:101], v[174:177], v[190:193], v[98:101]
	v_mfma_f32_16x16x32_bf16 v[86:89], v[166:169], v[198:201], v[86:89]
	v_mfma_f32_16x16x32_bf16 v[82:85], v[174:177], v[198:201], v[82:85]
	v_mfma_f32_16x16x32_bf16 v[70:73], v[166:169], v[206:209], v[70:73]
	v_mfma_f32_16x16x32_bf16 v[66:69], v[174:177], v[206:209], v[66:69]
	s_barrier
	s_setprio 0
	s_add_i32 s8, s10, s34
	v_lshl_add_u64 v[210:211], v[210:211], 0, s[82:83]
	s_mov_b32 m0, s8
	s_nop 0
	global_load_lds_dwordx4 v[210:211], off
	s_add_i32 m0, s8, 0x2000
	s_add_u32 s8, s28, 0x40080
	v_lshl_add_u64 v[210:211], v[212:213], 0, s[82:83]
	s_addc_u32 s9, s29, 0
	s_add_i32 s10, s11, s34
	global_load_lds_dwordx4 v[210:211], off
	v_lshl_add_u64 v[210:211], s[8:9], 0, v[130:131]
	s_mov_b32 m0, s10
	s_nop 0
	global_load_lds_dwordx4 v[210:211], off
	v_lshl_add_u64 v[210:211], s[8:9], 0, v[132:133]
	s_add_i32 m0, s10, 0x2000
	s_nop 0
	global_load_lds_dwordx4 v[210:211], off
	v_lshl_add_u64 v[210:211], v[214:215], 0, s[82:83]
	s_mov_b32 m0, s66
	s_nop 0
	global_load_lds_dwordx4 v[210:211], off
	v_lshl_add_u64 v[210:211], v[216:217], 0, s[82:83]
	s_mov_b32 m0, s67
	s_nop 0
	global_load_lds_dwordx4 v[210:211], off
	ds_read_b128 v[178:181], v145 offset:49152
	ds_read_b128 v[182:185], v145 offset:50176
	ds_read_b128 v[186:189], v145 offset:51200
	ds_read_b128 v[190:193], v145 offset:52224
	ds_read_b128 v[194:197], v145 offset:53248
	ds_read_b128 v[198:201], v145 offset:54272
	ds_read_b128 v[202:205], v145 offset:55296
	ds_read_b128 v[206:209], v145 offset:56320
	s_waitcnt vmcnt(8)
	s_waitcnt lgkmcnt(0)
	s_setprio 1
	s_barrier
	v_mfma_f32_16x16x32_bf16 v[62:65], v[146:149], v[178:181], v[62:65]
	v_mfma_f32_16x16x32_bf16 v[58:61], v[154:157], v[178:181], v[58:61]
	v_mfma_f32_16x16x32_bf16 v[46:49], v[146:149], v[186:189], v[46:49]
	v_mfma_f32_16x16x32_bf16 v[42:45], v[154:157], v[186:189], v[42:45]
	v_mfma_f32_16x16x32_bf16 v[30:33], v[146:149], v[194:197], v[30:33]
	v_mfma_f32_16x16x32_bf16 v[26:29], v[154:157], v[194:197], v[26:29]
	v_mfma_f32_16x16x32_bf16 v[14:17], v[146:149], v[202:205], v[14:17]
	v_mfma_f32_16x16x32_bf16 v[10:13], v[154:157], v[202:205], v[10:13]
	v_mfma_f32_16x16x32_bf16 v[62:65], v[150:153], v[182:185], v[62:65]
	v_mfma_f32_16x16x32_bf16 v[58:61], v[158:161], v[182:185], v[58:61]
	v_mfma_f32_16x16x32_bf16 v[46:49], v[150:153], v[190:193], v[46:49]
	v_mfma_f32_16x16x32_bf16 v[42:45], v[158:161], v[190:193], v[42:45]
	v_mfma_f32_16x16x32_bf16 v[30:33], v[150:153], v[198:201], v[30:33]
	v_mfma_f32_16x16x32_bf16 v[26:29], v[158:161], v[198:201], v[26:29]
	v_mfma_f32_16x16x32_bf16 v[14:17], v[150:153], v[206:209], v[14:17]
	v_mfma_f32_16x16x32_bf16 v[10:13], v[158:161], v[206:209], v[10:13]
	v_mfma_f32_16x16x32_bf16 v[54:57], v[162:165], v[178:181], v[54:57]
	v_mfma_f32_16x16x32_bf16 v[50:53], v[170:173], v[178:181], v[50:53]
	v_mfma_f32_16x16x32_bf16 v[38:41], v[162:165], v[186:189], v[38:41]
	v_mfma_f32_16x16x32_bf16 v[34:37], v[170:173], v[186:189], v[34:37]
	v_mfma_f32_16x16x32_bf16 v[22:25], v[162:165], v[194:197], v[22:25]
	v_mfma_f32_16x16x32_bf16 v[18:21], v[170:173], v[194:197], v[18:21]
	v_mfma_f32_16x16x32_bf16 v[6:9], v[162:165], v[202:205], v[6:9]
	v_mfma_f32_16x16x32_bf16 v[2:5], v[170:173], v[202:205], v[2:5]
	v_mfma_f32_16x16x32_bf16 v[54:57], v[166:169], v[182:185], v[54:57]
	v_mfma_f32_16x16x32_bf16 v[50:53], v[174:177], v[182:185], v[50:53]
	v_mfma_f32_16x16x32_bf16 v[38:41], v[166:169], v[190:193], v[38:41]
	v_mfma_f32_16x16x32_bf16 v[34:37], v[174:177], v[190:193], v[34:37]
	v_mfma_f32_16x16x32_bf16 v[22:25], v[166:169], v[198:201], v[22:25]
	v_mfma_f32_16x16x32_bf16 v[18:21], v[174:177], v[198:201], v[18:21]
	v_mfma_f32_16x16x32_bf16 v[6:9], v[166:169], v[206:209], v[6:9]
	v_mfma_f32_16x16x32_bf16 v[2:5], v[174:177], v[206:209], v[2:5]
	s_barrier
	s_setprio 0
	s_add_i32 s84, s84, 2
	s_add_u32 s60, s60, 0x100
	s_addc_u32 s61, s61, 0
	s_add_u32 s76, s76, 0x100
	s_addc_u32 s77, s77, 0
	s_cmp_gt_u32 s84, 13
	s_cbranch_scc0 .LBB0_497
	s_and_b64 vcc, exec, s[50:51]
	s_cbranch_vccz .LBB0_500
	s_barrier
